# EpiRes (out-proj and MLP-down epilogue) rewritten by hand: scalar-base 32-bit addressing, 16 loads up front, per-row counted waits; on v096
# baseline (speedup 1.0000x reference)
; __device__ __forceinline__ u32x4 pack8(const f32x4 v0, const f32x4 v1) { u32x4 w; w.x = cvt_pk_bf16(v0[0], v0[1]); w.y = cvt_pk_bf16(v0[2], v0[3]); w.z = cvt_pk_bf16(v1[0], v1[1]); w.w = cvt_pk_bf16(v1[2], v1[3]); return w; }
; __device__ __forceinline__ float sumsq8(const f32x4 a, const f32x4 b) { return ((a[0] * a[0] + a[1] * a[1]) + (a[2] * a[2] + a[3] * a[3])) + ((b[0] * b[0] + b[1] * b[1]) + (b[2] * b[2] + b[3] * b[3])); }
; __device__ __forceinline__ void unpack8(const u32x4 w, f32x4& a, f32x4& b) { a = (f32x4){bf_lo(w.x), bf_hi(w.x), bf_lo(w.y), bf_hi(w.y)}; b = (f32x4){bf_lo(w.z), bf_hi(w.z), bf_lo(w.w), bf_hi(w.w)}; }
;     __device__ __forceinline__ void operator()(const f32x4 (&acc)[2][2][4][2], const Unit& u, int wr, int wc, int fr, int fq) const {
;         const int row0 = u.pm * BM + wr * 64 + fr, col0 = u.pn * BM + wc * 32 + 8 * fq;
;         u32x4 rv[8][2];
; #pragma unroll
;         for (int i = 0; i < 8; ++i)
; #pragma unroll
;             for (int bj = 0; bj < 2; ++bj) rv[i][bj] = *(const u32x4*)(Rin + (size_t)(row0 + (i >> 2) * HALF + (i & 3) * 16) * DMODEL + col0 + bj * HALF);
; #pragma unroll
;         for (int ai = 0; ai < 2; ++ai)
; #pragma unroll
;             for (int m = 0; m < 4; ++m) { const int row = row0 + ai * HALF + m * 16; float part = 0.f;
; #pragma unroll
;                 for (int bj = 0; bj < 2; ++bj) { f32x4 r0, r1; unpack8(rv[ai * 4 + m][bj], r0, r1);
;                     const f32x4 h0 = r0 + acc[ai][bj][m][0], h1 = r1 + acc[ai][bj][m][1]; part += sumsq8(h0, h1);
;                     *(u32x4*)(XBo + (size_t)row * DMODEL + col0 + bj * HALF) = pack8(h0, h1); }
;                 part += __shfl_xor(part, 16); part += __shfl_xor(part, 32);
;                 if (fq == 0) ssq[(size_t)row * 16 + u.pn * 4 + wc] = part; }
;     }
.LBB0_517:
	v_readfirstlane_b32 s0, v192
	v_and_b32_e32 v224, 15, v192
	s_bfe_u32 s17, s0, 0x20006
	s_lshr_b32 s0, s0, 8
	s_lshl_b32 s0, s0, 6
	s_lshl_b32 s1, s40, 8
	s_add_i32 s0, s0, s1
	v_add_u32_e32 v224, s0, v224
	v_bfe_u32 v225, v192, 4, 2
	s_lshl_b32 s0, s26, 8
	s_lshl_b32 s1, s17, 5
	s_or_b32 s0, s0, s1
	v_lshl_or_b32 v232, v225, 3, s0
	v_lshlrev_b32_e32 v226, 11, v224
	v_lshl_add_u32 v226, v232, 1, v226
	v_mov_b32_e32 v230, v226
	global_load_dwordx4 v[116:119], v230, s[6:7]
	global_load_dwordx4 v[120:123], v230, s[6:7] offset:256
	v_add_u32_e32 v230, 0x8000, v226
	global_load_dwordx4 v[128:131], v230, s[6:7]
	global_load_dwordx4 v[132:135], v230, s[6:7] offset:256
	v_add_u32_e32 v230, 0x10000, v226
	global_load_dwordx4 v[136:139], v230, s[6:7]
	global_load_dwordx4 v[140:143], v230, s[6:7] offset:256
	v_add_u32_e32 v230, 0x18000, v226
	global_load_dwordx4 v[144:147], v230, s[6:7]
	global_load_dwordx4 v[156:159], v230, s[6:7] offset:256
	v_add_u32_e32 v230, 0x40000, v226
	global_load_dwordx4 v[160:163], v230, s[6:7]
	global_load_dwordx4 v[164:167], v230, s[6:7] offset:256
	v_add_u32_e32 v230, 0x48000, v226
	global_load_dwordx4 v[168:171], v230, s[6:7]
	global_load_dwordx4 v[172:175], v230, s[6:7] offset:256
	v_add_u32_e32 v230, 0x50000, v226
	global_load_dwordx4 v[176:179], v230, s[6:7]
	global_load_dwordx4 v[180:183], v230, s[6:7] offset:256
	v_add_u32_e32 v230, 0x58000, v226
	global_load_dwordx4 v[184:187], v230, s[6:7]
	global_load_dwordx4 v[188:191], v230, s[6:7] offset:256
	v_lshlrev_b32_e32 v227, 6, v224
	s_lshl_b32 s26, s26, 2
	s_ashr_i32 s27, s26, 31
	s_lshl_b32 s72, s17, 2
	s_lshl_b32 s0, s26, 2
	s_add_i32 s0, s0, s72
	v_add_u32_e32 v227, s0, v227
	v_cmp_eq_u32_e32 vcc, 0, v225
	v_xor_b32_e32 v228, 16, v241
	v_xor_b32_e32 v229, 32, v241
	v_lshlrev_b32_e32 v228, 2, v228
	v_lshlrev_b32_e32 v229, 2, v229
	s_waitcnt vmcnt(14)
	v_lshlrev_b32_e32 v214, 16, v116
	v_and_b32_e32 v215, 0xffff0000, v116
	v_lshlrev_b32_e32 v216, 16, v117
	v_and_b32_e32 v217, 0xffff0000, v117
	v_add_f32_e32 v152, v152, v214
	v_add_f32_e32 v153, v153, v215
	v_add_f32_e32 v154, v154, v216
	v_add_f32_e32 v155, v155, v217
	v_mul_f32_e32 v218, v153, v153
	v_mul_f32_e32 v219, v155, v155
	v_fmac_f32_e32 v218, v152, v152
	v_fmac_f32_e32 v219, v154, v154
	v_add_f32_e32 v220, v218, v219
	v_lshlrev_b32_e32 v214, 16, v118
	v_and_b32_e32 v215, 0xffff0000, v118
	v_lshlrev_b32_e32 v216, 16, v119
	v_and_b32_e32 v217, 0xffff0000, v119
	v_add_f32_e32 v148, v148, v214
	v_add_f32_e32 v149, v149, v215
	v_add_f32_e32 v150, v150, v216
	v_add_f32_e32 v151, v151, v217
	v_mul_f32_e32 v218, v149, v149
	v_mul_f32_e32 v219, v151, v151
	v_fmac_f32_e32 v218, v148, v148
	v_fmac_f32_e32 v219, v150, v150
	v_add_f32_e32 v221, v218, v219
	v_cvt_pk_bf16_f32 v152, v152, v153
	v_cvt_pk_bf16_f32 v153, v154, v155
	v_cvt_pk_bf16_f32 v154, v148, v149
	v_cvt_pk_bf16_f32 v155, v150, v151
	v_mov_b32_e32 v230, v226
	global_store_dwordx4 v230, v[152:155], s[10:11]
	v_lshlrev_b32_e32 v214, 16, v120
	v_and_b32_e32 v215, 0xffff0000, v120
	v_lshlrev_b32_e32 v216, 16, v121
	v_and_b32_e32 v217, 0xffff0000, v121
	v_add_f32_e32 v124, v124, v214
	v_add_f32_e32 v125, v125, v215
	v_add_f32_e32 v126, v126, v216
	v_add_f32_e32 v127, v127, v217
	v_mul_f32_e32 v218, v125, v125
	v_mul_f32_e32 v219, v127, v127
	v_fmac_f32_e32 v218, v124, v124
	v_fmac_f32_e32 v219, v126, v126
	v_add_f32_e32 v222, v218, v219
	v_lshlrev_b32_e32 v214, 16, v122
	v_and_b32_e32 v215, 0xffff0000, v122
	v_lshlrev_b32_e32 v216, 16, v123
	v_and_b32_e32 v217, 0xffff0000, v123
	v_add_f32_e32 v112, v112, v214
	v_add_f32_e32 v113, v113, v215
	v_add_f32_e32 v114, v114, v216
	v_add_f32_e32 v115, v115, v217
	v_mul_f32_e32 v218, v113, v113
	v_mul_f32_e32 v219, v115, v115
	v_fmac_f32_e32 v218, v112, v112
	v_fmac_f32_e32 v219, v114, v114
	v_add_f32_e32 v223, v218, v219
	v_cvt_pk_bf16_f32 v124, v124, v125
	v_cvt_pk_bf16_f32 v125, v126, v127
	v_cvt_pk_bf16_f32 v126, v112, v113
	v_cvt_pk_bf16_f32 v127, v114, v115
	global_store_dwordx4 v230, v[124:127], s[10:11] offset:256
	v_add_f32_e32 v220, v220, v221
	v_add_f32_e32 v222, v222, v223
	v_add_f32_e32 v224, v220, v222
	ds_bpermute_b32 v225, v228, v224
	v_mov_b32_e32 v231, v227
	s_waitcnt lgkmcnt(0)
	v_add_f32_e32 v224, v224, v225
	ds_bpermute_b32 v225, v229, v224
	s_waitcnt lgkmcnt(0)
	v_add_f32_e32 v224, v224, v225
	s_and_saveexec_b64 s[0:1], vcc
	global_store_dword v231, v224, s[12:13]
	s_or_b64 exec, exec, s[0:1]
	s_waitcnt vmcnt(15)
	v_lshlrev_b32_e32 v214, 16, v128
	v_and_b32_e32 v215, 0xffff0000, v128
	v_lshlrev_b32_e32 v216, 16, v129
	v_and_b32_e32 v217, 0xffff0000, v129
	v_add_f32_e32 v108, v108, v214
	v_add_f32_e32 v109, v109, v215
	v_add_f32_e32 v110, v110, v216
	v_add_f32_e32 v111, v111, v217
	v_mul_f32_e32 v218, v109, v109
	v_mul_f32_e32 v219, v111, v111
	v_fmac_f32_e32 v218, v108, v108
	v_fmac_f32_e32 v219, v110, v110
	v_add_f32_e32 v220, v218, v219
	v_lshlrev_b32_e32 v214, 16, v130
	v_and_b32_e32 v215, 0xffff0000, v130
	v_lshlrev_b32_e32 v216, 16, v131
	v_and_b32_e32 v217, 0xffff0000, v131
	v_add_f32_e32 v104, v104, v214
	v_add_f32_e32 v105, v105, v215
	v_add_f32_e32 v106, v106, v216
	v_add_f32_e32 v107, v107, v217
	v_mul_f32_e32 v218, v105, v105
	v_mul_f32_e32 v219, v107, v107
	v_fmac_f32_e32 v218, v104, v104
	v_fmac_f32_e32 v219, v106, v106
	v_add_f32_e32 v221, v218, v219
	v_cvt_pk_bf16_f32 v108, v108, v109
	v_cvt_pk_bf16_f32 v109, v110, v111
	v_cvt_pk_bf16_f32 v110, v104, v105
	v_cvt_pk_bf16_f32 v111, v106, v107
	v_add_u32_e32 v230, 0x8000, v226
	global_store_dwordx4 v230, v[108:111], s[10:11]
	v_lshlrev_b32_e32 v214, 16, v132
	v_and_b32_e32 v215, 0xffff0000, v132
	v_lshlrev_b32_e32 v216, 16, v133
	v_and_b32_e32 v217, 0xffff0000, v133
	v_add_f32_e32 v100, v100, v214
	v_add_f32_e32 v101, v101, v215
	v_add_f32_e32 v102, v102, v216
	v_add_f32_e32 v103, v103, v217
	v_mul_f32_e32 v218, v101, v101
	v_mul_f32_e32 v219, v103, v103
	v_fmac_f32_e32 v218, v100, v100
	v_fmac_f32_e32 v219, v102, v102
	v_add_f32_e32 v222, v218, v219
	v_lshlrev_b32_e32 v214, 16, v134
	v_and_b32_e32 v215, 0xffff0000, v134
	v_lshlrev_b32_e32 v216, 16, v135
	v_and_b32_e32 v217, 0xffff0000, v135
	v_add_f32_e32 v96, v96, v214
	v_add_f32_e32 v97, v97, v215
	v_add_f32_e32 v98, v98, v216
	v_add_f32_e32 v99, v99, v217
	v_mul_f32_e32 v218, v97, v97
	v_mul_f32_e32 v219, v99, v99
	v_fmac_f32_e32 v218, v96, v96
	v_fmac_f32_e32 v219, v98, v98
	v_add_f32_e32 v223, v218, v219
	v_cvt_pk_bf16_f32 v100, v100, v101
	v_cvt_pk_bf16_f32 v101, v102, v103
	v_cvt_pk_bf16_f32 v102, v96, v97
	v_cvt_pk_bf16_f32 v103, v98, v99
	global_store_dwordx4 v230, v[100:103], s[10:11] offset:256
	v_add_f32_e32 v220, v220, v221
	v_add_f32_e32 v222, v222, v223
	v_add_f32_e32 v224, v220, v222
	ds_bpermute_b32 v225, v228, v224
	v_add_u32_e32 v231, 0x400, v227
	s_waitcnt lgkmcnt(0)
; __device__ __forceinline__ u32x4 pack8(const f32x4 v0, const f32x4 v1) { u32x4 w; w.x = cvt_pk_bf16(v0[0], v0[1]); w.y = cvt_pk_bf16(v0[2], v0[3]); w.z = cvt_pk_bf16(v1[0], v1[1]); w.w = cvt_pk_bf16(v1[2], v1[3]); return w; }
; __device__ __forceinline__ float sumsq8(const f32x4 a, const f32x4 b) { return ((a[0] * a[0] + a[1] * a[1]) + (a[2] * a[2] + a[3] * a[3])) + ((b[0] * b[0] + b[1] * b[1]) + (b[2] * b[2] + b[3] * b[3])); }
; __device__ __forceinline__ void unpack8(const u32x4 w, f32x4& a, f32x4& b) { a = (f32x4){bf_lo(w.x), bf_hi(w.x), bf_lo(w.y), bf_hi(w.y)}; b = (f32x4){bf_lo(w.z), bf_hi(w.z), bf_lo(w.w), bf_hi(w.w)}; }
;     __device__ __forceinline__ void operator()(const f32x4 (&acc)[2][2][4][2], const Unit& u, int wr, int wc, int fr, int fq) const {
;     ...
;             for (int m = 0; m < 4; ++m) { const int row = row0 + ai * HALF + m * 16; float part = 0.f;
; #pragma unroll
;                 for (int bj = 0; bj < 2; ++bj) { f32x4 r0, r1; unpack8(rv[ai * 4 + m][bj], r0, r1);
;                     const f32x4 h0 = r0 + acc[ai][bj][m][0], h1 = r1 + acc[ai][bj][m][1]; part += sumsq8(h0, h1);
;                     *(u32x4*)(XBo + (size_t)row * DMODEL + col0 + bj * HALF) = pack8(h0, h1); }
;                 part += __shfl_xor(part, 16); part += __shfl_xor(part, 32);
;                 if (fq == 0) ssq[(size_t)row * 16 + u.pn * 4 + wc] = part; }
	v_add_f32_e32 v224, v224, v225
	ds_bpermute_b32 v225, v229, v224
	s_waitcnt lgkmcnt(0)
	v_add_f32_e32 v224, v224, v225
	s_and_saveexec_b64 s[0:1], vcc
	global_store_dword v231, v224, s[12:13]
	s_or_b64 exec, exec, s[0:1]
	s_waitcnt vmcnt(16)
	v_lshlrev_b32_e32 v214, 16, v136
	v_and_b32_e32 v215, 0xffff0000, v136
	v_lshlrev_b32_e32 v216, 16, v137
	v_and_b32_e32 v217, 0xffff0000, v137
	v_add_f32_e32 v92, v92, v214
	v_add_f32_e32 v93, v93, v215
	v_add_f32_e32 v94, v94, v216
	v_add_f32_e32 v95, v95, v217
	v_mul_f32_e32 v218, v93, v93
	v_mul_f32_e32 v219, v95, v95
	v_fmac_f32_e32 v218, v92, v92
	v_fmac_f32_e32 v219, v94, v94
	v_add_f32_e32 v220, v218, v219
	v_lshlrev_b32_e32 v214, 16, v138
	v_and_b32_e32 v215, 0xffff0000, v138
	v_lshlrev_b32_e32 v216, 16, v139
	v_and_b32_e32 v217, 0xffff0000, v139
	v_add_f32_e32 v88, v88, v214
	v_add_f32_e32 v89, v89, v215
	v_add_f32_e32 v90, v90, v216
	v_add_f32_e32 v91, v91, v217
	v_mul_f32_e32 v218, v89, v89
	v_mul_f32_e32 v219, v91, v91
	v_fmac_f32_e32 v218, v88, v88
	v_fmac_f32_e32 v219, v90, v90
	v_add_f32_e32 v221, v218, v219
	v_cvt_pk_bf16_f32 v92, v92, v93
	v_cvt_pk_bf16_f32 v93, v94, v95
	v_cvt_pk_bf16_f32 v94, v88, v89
	v_cvt_pk_bf16_f32 v95, v90, v91
	v_add_u32_e32 v230, 0x10000, v226
	global_store_dwordx4 v230, v[92:95], s[10:11]
	v_lshlrev_b32_e32 v214, 16, v140
	v_and_b32_e32 v215, 0xffff0000, v140
	v_lshlrev_b32_e32 v216, 16, v141
	v_and_b32_e32 v217, 0xffff0000, v141
	v_add_f32_e32 v84, v84, v214
	v_add_f32_e32 v85, v85, v215
	v_add_f32_e32 v86, v86, v216
	v_add_f32_e32 v87, v87, v217
	v_mul_f32_e32 v218, v85, v85
	v_mul_f32_e32 v219, v87, v87
	v_fmac_f32_e32 v218, v84, v84
	v_fmac_f32_e32 v219, v86, v86
	v_add_f32_e32 v222, v218, v219
	v_lshlrev_b32_e32 v214, 16, v142
	v_and_b32_e32 v215, 0xffff0000, v142
	v_lshlrev_b32_e32 v216, 16, v143
	v_and_b32_e32 v217, 0xffff0000, v143
	v_add_f32_e32 v80, v80, v214
	v_add_f32_e32 v81, v81, v215
	v_add_f32_e32 v82, v82, v216
	v_add_f32_e32 v83, v83, v217
	v_mul_f32_e32 v218, v81, v81
	v_mul_f32_e32 v219, v83, v83
	v_fmac_f32_e32 v218, v80, v80
	v_fmac_f32_e32 v219, v82, v82
	v_add_f32_e32 v223, v218, v219
	v_cvt_pk_bf16_f32 v84, v84, v85
	v_cvt_pk_bf16_f32 v85, v86, v87
	v_cvt_pk_bf16_f32 v86, v80, v81
	v_cvt_pk_bf16_f32 v87, v82, v83
	global_store_dwordx4 v230, v[84:87], s[10:11] offset:256
	v_add_f32_e32 v220, v220, v221
	v_add_f32_e32 v222, v222, v223
	v_add_f32_e32 v224, v220, v222
	ds_bpermute_b32 v225, v228, v224
	v_add_u32_e32 v231, 0x800, v227
	s_waitcnt lgkmcnt(0)
	v_add_f32_e32 v224, v224, v225
	ds_bpermute_b32 v225, v229, v224
	s_waitcnt lgkmcnt(0)
	v_add_f32_e32 v224, v224, v225
	s_and_saveexec_b64 s[0:1], vcc
	global_store_dword v231, v224, s[12:13]
	s_or_b64 exec, exec, s[0:1]
	s_waitcnt vmcnt(17)
	v_lshlrev_b32_e32 v214, 16, v144
	v_and_b32_e32 v215, 0xffff0000, v144
	v_lshlrev_b32_e32 v216, 16, v145
	v_and_b32_e32 v217, 0xffff0000, v145
	v_add_f32_e32 v76, v76, v214
	v_add_f32_e32 v77, v77, v215
	v_add_f32_e32 v78, v78, v216
	v_add_f32_e32 v79, v79, v217
	v_mul_f32_e32 v218, v77, v77
	v_mul_f32_e32 v219, v79, v79
	v_fmac_f32_e32 v218, v76, v76
	v_fmac_f32_e32 v219, v78, v78
	v_add_f32_e32 v220, v218, v219
	v_lshlrev_b32_e32 v214, 16, v146
	v_and_b32_e32 v215, 0xffff0000, v146
	v_lshlrev_b32_e32 v216, 16, v147
	v_and_b32_e32 v217, 0xffff0000, v147
	v_add_f32_e32 v72, v72, v214
	v_add_f32_e32 v73, v73, v215
	v_add_f32_e32 v74, v74, v216
	v_add_f32_e32 v75, v75, v217
	v_mul_f32_e32 v218, v73, v73
	v_mul_f32_e32 v219, v75, v75
	v_fmac_f32_e32 v218, v72, v72
	v_fmac_f32_e32 v219, v74, v74
	v_add_f32_e32 v221, v218, v219
	v_cvt_pk_bf16_f32 v76, v76, v77
	v_cvt_pk_bf16_f32 v77, v78, v79
	v_cvt_pk_bf16_f32 v78, v72, v73
	v_cvt_pk_bf16_f32 v79, v74, v75
	v_add_u32_e32 v230, 0x18000, v226
	global_store_dwordx4 v230, v[76:79], s[10:11]
	v_lshlrev_b32_e32 v214, 16, v156
	v_and_b32_e32 v215, 0xffff0000, v156
	v_lshlrev_b32_e32 v216, 16, v157
	v_and_b32_e32 v217, 0xffff0000, v157
	v_add_f32_e32 v68, v68, v214
	v_add_f32_e32 v69, v69, v215
	v_add_f32_e32 v70, v70, v216
	v_add_f32_e32 v71, v71, v217
	v_mul_f32_e32 v218, v69, v69
	v_mul_f32_e32 v219, v71, v71
	v_fmac_f32_e32 v218, v68, v68
	v_fmac_f32_e32 v219, v70, v70
	v_add_f32_e32 v222, v218, v219
	v_lshlrev_b32_e32 v214, 16, v158
	v_and_b32_e32 v215, 0xffff0000, v158
	v_lshlrev_b32_e32 v216, 16, v159
	v_and_b32_e32 v217, 0xffff0000, v159
	v_add_f32_e32 v64, v64, v214
	v_add_f32_e32 v65, v65, v215
	v_add_f32_e32 v66, v66, v216
	v_add_f32_e32 v67, v67, v217
	v_mul_f32_e32 v218, v65, v65
	v_mul_f32_e32 v219, v67, v67
	v_fmac_f32_e32 v218, v64, v64
	v_fmac_f32_e32 v219, v66, v66
	v_add_f32_e32 v223, v218, v219
	v_cvt_pk_bf16_f32 v68, v68, v69
	v_cvt_pk_bf16_f32 v69, v70, v71
	v_cvt_pk_bf16_f32 v70, v64, v65
	v_cvt_pk_bf16_f32 v71, v66, v67
	global_store_dwordx4 v230, v[68:71], s[10:11] offset:256
	v_add_f32_e32 v220, v220, v221
	v_add_f32_e32 v222, v222, v223
	v_add_f32_e32 v224, v220, v222
	ds_bpermute_b32 v225, v228, v224
	v_add_u32_e32 v231, 0xc00, v227
	s_waitcnt lgkmcnt(0)
	v_add_f32_e32 v224, v224, v225
	ds_bpermute_b32 v225, v229, v224
	s_waitcnt lgkmcnt(0)
	v_add_f32_e32 v224, v224, v225
	s_and_saveexec_b64 s[0:1], vcc
	global_store_dword v231, v224, s[12:13]
	s_or_b64 exec, exec, s[0:1]
	s_waitcnt vmcnt(18)
; __device__ __forceinline__ u32x4 pack8(const f32x4 v0, const f32x4 v1) { u32x4 w; w.x = cvt_pk_bf16(v0[0], v0[1]); w.y = cvt_pk_bf16(v0[2], v0[3]); w.z = cvt_pk_bf16(v1[0], v1[1]); w.w = cvt_pk_bf16(v1[2], v1[3]); return w; }
; __device__ __forceinline__ float sumsq8(const f32x4 a, const f32x4 b) { return ((a[0] * a[0] + a[1] * a[1]) + (a[2] * a[2] + a[3] * a[3])) + ((b[0] * b[0] + b[1] * b[1]) + (b[2] * b[2] + b[3] * b[3])); }
; __device__ __forceinline__ void unpack8(const u32x4 w, f32x4& a, f32x4& b) { a = (f32x4){bf_lo(w.x), bf_hi(w.x), bf_lo(w.y), bf_hi(w.y)}; b = (f32x4){bf_lo(w.z), bf_hi(w.z), bf_lo(w.w), bf_hi(w.w)}; }
;     __device__ __forceinline__ void operator()(const f32x4 (&acc)[2][2][4][2], const Unit& u, int wr, int wc, int fr, int fq) const {
;     ...
;             for (int m = 0; m < 4; ++m) { const int row = row0 + ai * HALF + m * 16; float part = 0.f;
; #pragma unroll
;                 for (int bj = 0; bj < 2; ++bj) { f32x4 r0, r1; unpack8(rv[ai * 4 + m][bj], r0, r1);
;                     const f32x4 h0 = r0 + acc[ai][bj][m][0], h1 = r1 + acc[ai][bj][m][1]; part += sumsq8(h0, h1);
;                     *(u32x4*)(XBo + (size_t)row * DMODEL + col0 + bj * HALF) = pack8(h0, h1); }
;                 part += __shfl_xor(part, 16); part += __shfl_xor(part, 32);
;                 if (fq == 0) ssq[(size_t)row * 16 + u.pn * 4 + wc] = part; }
	v_lshlrev_b32_e32 v214, 16, v160
	v_and_b32_e32 v215, 0xffff0000, v160
	v_lshlrev_b32_e32 v216, 16, v161
	v_and_b32_e32 v217, 0xffff0000, v161
	v_add_f32_e32 v60, v60, v214
	v_add_f32_e32 v61, v61, v215
	v_add_f32_e32 v62, v62, v216
	v_add_f32_e32 v63, v63, v217
	v_mul_f32_e32 v218, v61, v61
	v_mul_f32_e32 v219, v63, v63
	v_fmac_f32_e32 v218, v60, v60
	v_fmac_f32_e32 v219, v62, v62
	v_add_f32_e32 v220, v218, v219
	v_lshlrev_b32_e32 v214, 16, v162
	v_and_b32_e32 v215, 0xffff0000, v162
	v_lshlrev_b32_e32 v216, 16, v163
	v_and_b32_e32 v217, 0xffff0000, v163
	v_add_f32_e32 v56, v56, v214
	v_add_f32_e32 v57, v57, v215
	v_add_f32_e32 v58, v58, v216
	v_add_f32_e32 v59, v59, v217
	v_mul_f32_e32 v218, v57, v57
	v_mul_f32_e32 v219, v59, v59
	v_fmac_f32_e32 v218, v56, v56
	v_fmac_f32_e32 v219, v58, v58
	v_add_f32_e32 v221, v218, v219
	v_cvt_pk_bf16_f32 v60, v60, v61
	v_cvt_pk_bf16_f32 v61, v62, v63
	v_cvt_pk_bf16_f32 v62, v56, v57
	v_cvt_pk_bf16_f32 v63, v58, v59
	v_add_u32_e32 v230, 0x40000, v226
	global_store_dwordx4 v230, v[60:63], s[10:11]
	v_lshlrev_b32_e32 v214, 16, v164
	v_and_b32_e32 v215, 0xffff0000, v164
	v_lshlrev_b32_e32 v216, 16, v165
	v_and_b32_e32 v217, 0xffff0000, v165
	v_add_f32_e32 v52, v52, v214
	v_add_f32_e32 v53, v53, v215
	v_add_f32_e32 v54, v54, v216
	v_add_f32_e32 v55, v55, v217
	v_mul_f32_e32 v218, v53, v53
	v_mul_f32_e32 v219, v55, v55
	v_fmac_f32_e32 v218, v52, v52
	v_fmac_f32_e32 v219, v54, v54
	v_add_f32_e32 v222, v218, v219
	v_lshlrev_b32_e32 v214, 16, v166
	v_and_b32_e32 v215, 0xffff0000, v166
	v_lshlrev_b32_e32 v216, 16, v167
	v_and_b32_e32 v217, 0xffff0000, v167
	v_add_f32_e32 v48, v48, v214
	v_add_f32_e32 v49, v49, v215
	v_add_f32_e32 v50, v50, v216
	v_add_f32_e32 v51, v51, v217
	v_mul_f32_e32 v218, v49, v49
	v_mul_f32_e32 v219, v51, v51
	v_fmac_f32_e32 v218, v48, v48
	v_fmac_f32_e32 v219, v50, v50
	v_add_f32_e32 v223, v218, v219
	v_cvt_pk_bf16_f32 v52, v52, v53
	v_cvt_pk_bf16_f32 v53, v54, v55
	v_cvt_pk_bf16_f32 v54, v48, v49
	v_cvt_pk_bf16_f32 v55, v50, v51
	global_store_dwordx4 v230, v[52:55], s[10:11] offset:256
	v_add_f32_e32 v220, v220, v221
	v_add_f32_e32 v222, v222, v223
	v_add_f32_e32 v224, v220, v222
	ds_bpermute_b32 v225, v228, v224
	v_add_u32_e32 v231, 0x2000, v227
	s_waitcnt lgkmcnt(0)
	v_add_f32_e32 v224, v224, v225
	ds_bpermute_b32 v225, v229, v224
	s_waitcnt lgkmcnt(0)
	v_add_f32_e32 v224, v224, v225
	s_and_saveexec_b64 s[0:1], vcc
	global_store_dword v231, v224, s[12:13]
	s_or_b64 exec, exec, s[0:1]
	s_waitcnt vmcnt(19)
	v_lshlrev_b32_e32 v214, 16, v168
	v_and_b32_e32 v215, 0xffff0000, v168
	v_lshlrev_b32_e32 v216, 16, v169
	v_and_b32_e32 v217, 0xffff0000, v169
	v_add_f32_e32 v44, v44, v214
	v_add_f32_e32 v45, v45, v215
	v_add_f32_e32 v46, v46, v216
	v_add_f32_e32 v47, v47, v217
	v_mul_f32_e32 v218, v45, v45
	v_mul_f32_e32 v219, v47, v47
	v_fmac_f32_e32 v218, v44, v44
	v_fmac_f32_e32 v219, v46, v46
	v_add_f32_e32 v220, v218, v219
	v_lshlrev_b32_e32 v214, 16, v170
	v_and_b32_e32 v215, 0xffff0000, v170
	v_lshlrev_b32_e32 v216, 16, v171
	v_and_b32_e32 v217, 0xffff0000, v171
	v_add_f32_e32 v40, v40, v214
	v_add_f32_e32 v41, v41, v215
	v_add_f32_e32 v42, v42, v216
	v_add_f32_e32 v43, v43, v217
	v_mul_f32_e32 v218, v41, v41
	v_mul_f32_e32 v219, v43, v43
	v_fmac_f32_e32 v218, v40, v40
	v_fmac_f32_e32 v219, v42, v42
	v_add_f32_e32 v221, v218, v219
	v_cvt_pk_bf16_f32 v44, v44, v45
	v_cvt_pk_bf16_f32 v45, v46, v47
	v_cvt_pk_bf16_f32 v46, v40, v41
	v_cvt_pk_bf16_f32 v47, v42, v43
	v_add_u32_e32 v230, 0x48000, v226
	global_store_dwordx4 v230, v[44:47], s[10:11]
	v_lshlrev_b32_e32 v214, 16, v172
	v_and_b32_e32 v215, 0xffff0000, v172
	v_lshlrev_b32_e32 v216, 16, v173
	v_and_b32_e32 v217, 0xffff0000, v173
	v_add_f32_e32 v36, v36, v214
	v_add_f32_e32 v37, v37, v215
	v_add_f32_e32 v38, v38, v216
	v_add_f32_e32 v39, v39, v217
	v_mul_f32_e32 v218, v37, v37
	v_mul_f32_e32 v219, v39, v39
	v_fmac_f32_e32 v218, v36, v36
	v_fmac_f32_e32 v219, v38, v38
	v_add_f32_e32 v222, v218, v219
	v_lshlrev_b32_e32 v214, 16, v174
	v_and_b32_e32 v215, 0xffff0000, v174
	v_lshlrev_b32_e32 v216, 16, v175
	v_and_b32_e32 v217, 0xffff0000, v175
	v_add_f32_e32 v32, v32, v214
	v_add_f32_e32 v33, v33, v215
	v_add_f32_e32 v34, v34, v216
	v_add_f32_e32 v35, v35, v217
	v_mul_f32_e32 v218, v33, v33
	v_mul_f32_e32 v219, v35, v35
	v_fmac_f32_e32 v218, v32, v32
	v_fmac_f32_e32 v219, v34, v34
	v_add_f32_e32 v223, v218, v219
	v_cvt_pk_bf16_f32 v36, v36, v37
	v_cvt_pk_bf16_f32 v37, v38, v39
	v_cvt_pk_bf16_f32 v38, v32, v33
	v_cvt_pk_bf16_f32 v39, v34, v35
	global_store_dwordx4 v230, v[36:39], s[10:11] offset:256
	v_add_f32_e32 v220, v220, v221
	v_add_f32_e32 v222, v222, v223
	v_add_f32_e32 v224, v220, v222
	ds_bpermute_b32 v225, v228, v224
	v_add_u32_e32 v231, 0x2400, v227
	s_waitcnt lgkmcnt(0)
	v_add_f32_e32 v224, v224, v225
	ds_bpermute_b32 v225, v229, v224
	s_waitcnt lgkmcnt(0)
	v_add_f32_e32 v224, v224, v225
	s_and_saveexec_b64 s[0:1], vcc
	global_store_dword v231, v224, s[12:13]
	s_or_b64 exec, exec, s[0:1]
	s_waitcnt vmcnt(20)
; __device__ __forceinline__ u32x4 pack8(const f32x4 v0, const f32x4 v1) { u32x4 w; w.x = cvt_pk_bf16(v0[0], v0[1]); w.y = cvt_pk_bf16(v0[2], v0[3]); w.z = cvt_pk_bf16(v1[0], v1[1]); w.w = cvt_pk_bf16(v1[2], v1[3]); return w; }
; __device__ __forceinline__ float sumsq8(const f32x4 a, const f32x4 b) { return ((a[0] * a[0] + a[1] * a[1]) + (a[2] * a[2] + a[3] * a[3])) + ((b[0] * b[0] + b[1] * b[1]) + (b[2] * b[2] + b[3] * b[3])); }
; __device__ __forceinline__ void unpack8(const u32x4 w, f32x4& a, f32x4& b) { a = (f32x4){bf_lo(w.x), bf_hi(w.x), bf_lo(w.y), bf_hi(w.y)}; b = (f32x4){bf_lo(w.z), bf_hi(w.z), bf_lo(w.w), bf_hi(w.w)}; }
; #define PG8_BAR __builtin_amdgcn_s_barrier()
;     __device__ __forceinline__ void operator()(const f32x4 (&acc)[2][2][4][2], const Unit& u, int wr, int wc, int fr, int fq) const {
;     ...
;             for (int m = 0; m < 4; ++m) { const int row = row0 + ai * HALF + m * 16; float part = 0.f;
; #pragma unroll
;                 for (int bj = 0; bj < 2; ++bj) { f32x4 r0, r1; unpack8(rv[ai * 4 + m][bj], r0, r1);
;                     const f32x4 h0 = r0 + acc[ai][bj][m][0], h1 = r1 + acc[ai][bj][m][1]; part += sumsq8(h0, h1);
;                     *(u32x4*)(XBo + (size_t)row * DMODEL + col0 + bj * HALF) = pack8(h0, h1); }
;                 part += __shfl_xor(part, 16); part += __shfl_xor(part, 32);
;                 if (fq == 0) ssq[(size_t)row * 16 + u.pn * 4 + wc] = part; }
; template <class Epi, class Sched, bool ALIGN_EPI = false, bool SP2 = false>
; __device__ __forceinline__ void gemm_phase(PG8_LAS unsigned char* lds, const Gemm g, const Sched& S, const Epi& E) {
;     ...
;         if (!has_next) break;
; #pragma unroll
;         for (int a = 0; a < 2; ++a)
; #pragma unroll
;             for (int b = 0; b < 2; ++b)
; #pragma unroll
;                 for (int m = 0; m < 4; ++m)
; #pragma unroll
;                     for (int n = 0; n < 2; ++n) acc[a][b][m][n] = (f32x4){0.f, 0.f, 0.f, 0.f};
;         cur = nxt; cA = nA; cB = nB; ++ui; relax = Epi::LOADS_BEFORE_STORES && !Epi::AFTER_DRAIN && SP2;
;         if constexpr (ALIGN_EPI) { if (wr == 1) PG8_BAR; }
	v_lshlrev_b32_e32 v214, 16, v176
	v_and_b32_e32 v215, 0xffff0000, v176
	v_lshlrev_b32_e32 v216, 16, v177
	v_and_b32_e32 v217, 0xffff0000, v177
	v_add_f32_e32 v28, v28, v214
	v_add_f32_e32 v29, v29, v215
	v_add_f32_e32 v30, v30, v216
	v_add_f32_e32 v31, v31, v217
	v_mul_f32_e32 v218, v29, v29
	v_mul_f32_e32 v219, v31, v31
	v_fmac_f32_e32 v218, v28, v28
	v_fmac_f32_e32 v219, v30, v30
	v_add_f32_e32 v220, v218, v219
	v_lshlrev_b32_e32 v214, 16, v178
	v_and_b32_e32 v215, 0xffff0000, v178
	v_lshlrev_b32_e32 v216, 16, v179
	v_and_b32_e32 v217, 0xffff0000, v179
	v_add_f32_e32 v24, v24, v214
	v_add_f32_e32 v25, v25, v215
	v_add_f32_e32 v26, v26, v216
	v_add_f32_e32 v27, v27, v217
	v_mul_f32_e32 v218, v25, v25
	v_mul_f32_e32 v219, v27, v27
	v_fmac_f32_e32 v218, v24, v24
	v_fmac_f32_e32 v219, v26, v26
	v_add_f32_e32 v221, v218, v219
	v_cvt_pk_bf16_f32 v28, v28, v29
	v_cvt_pk_bf16_f32 v29, v30, v31
	v_cvt_pk_bf16_f32 v30, v24, v25
	v_cvt_pk_bf16_f32 v31, v26, v27
	v_add_u32_e32 v230, 0x50000, v226
	global_store_dwordx4 v230, v[28:31], s[10:11]
	v_lshlrev_b32_e32 v214, 16, v180
	v_and_b32_e32 v215, 0xffff0000, v180
	v_lshlrev_b32_e32 v216, 16, v181
	v_and_b32_e32 v217, 0xffff0000, v181
	v_add_f32_e32 v20, v20, v214
	v_add_f32_e32 v21, v21, v215
	v_add_f32_e32 v22, v22, v216
	v_add_f32_e32 v23, v23, v217
	v_mul_f32_e32 v218, v21, v21
	v_mul_f32_e32 v219, v23, v23
	v_fmac_f32_e32 v218, v20, v20
	v_fmac_f32_e32 v219, v22, v22
	v_add_f32_e32 v222, v218, v219
	v_lshlrev_b32_e32 v214, 16, v182
	v_and_b32_e32 v215, 0xffff0000, v182
	v_lshlrev_b32_e32 v216, 16, v183
	v_and_b32_e32 v217, 0xffff0000, v183
	v_add_f32_e32 v16, v16, v214
	v_add_f32_e32 v17, v17, v215
	v_add_f32_e32 v18, v18, v216
	v_add_f32_e32 v19, v19, v217
	v_mul_f32_e32 v218, v17, v17
	v_mul_f32_e32 v219, v19, v19
	v_fmac_f32_e32 v218, v16, v16
	v_fmac_f32_e32 v219, v18, v18
	v_add_f32_e32 v223, v218, v219
	v_cvt_pk_bf16_f32 v20, v20, v21
	v_cvt_pk_bf16_f32 v21, v22, v23
	v_cvt_pk_bf16_f32 v22, v16, v17
	v_cvt_pk_bf16_f32 v23, v18, v19
	global_store_dwordx4 v230, v[20:23], s[10:11] offset:256
	v_add_f32_e32 v220, v220, v221
	v_add_f32_e32 v222, v222, v223
	v_add_f32_e32 v224, v220, v222
	ds_bpermute_b32 v225, v228, v224
	v_add_u32_e32 v231, 0x2800, v227
	s_waitcnt lgkmcnt(0)
	v_add_f32_e32 v224, v224, v225
	ds_bpermute_b32 v225, v229, v224
	s_waitcnt lgkmcnt(0)
	v_add_f32_e32 v224, v224, v225
	s_and_saveexec_b64 s[0:1], vcc
	global_store_dword v231, v224, s[12:13]
	s_or_b64 exec, exec, s[0:1]
	s_waitcnt vmcnt(21)
	v_lshlrev_b32_e32 v214, 16, v184
	v_and_b32_e32 v215, 0xffff0000, v184
	v_lshlrev_b32_e32 v216, 16, v185
	v_and_b32_e32 v217, 0xffff0000, v185
	v_add_f32_e32 v12, v12, v214
	v_add_f32_e32 v13, v13, v215
	v_add_f32_e32 v14, v14, v216
	v_add_f32_e32 v15, v15, v217
	v_mul_f32_e32 v218, v13, v13
	v_mul_f32_e32 v219, v15, v15
	v_fmac_f32_e32 v218, v12, v12
	v_fmac_f32_e32 v219, v14, v14
	v_add_f32_e32 v220, v218, v219
	v_lshlrev_b32_e32 v214, 16, v186
	v_and_b32_e32 v215, 0xffff0000, v186
	v_lshlrev_b32_e32 v216, 16, v187
	v_and_b32_e32 v217, 0xffff0000, v187
	v_add_f32_e32 v8, v8, v214
	v_add_f32_e32 v9, v9, v215
	v_add_f32_e32 v10, v10, v216
	v_add_f32_e32 v11, v11, v217
	v_mul_f32_e32 v218, v9, v9
	v_mul_f32_e32 v219, v11, v11
	v_fmac_f32_e32 v218, v8, v8
	v_fmac_f32_e32 v219, v10, v10
	v_add_f32_e32 v221, v218, v219
	v_cvt_pk_bf16_f32 v12, v12, v13
	v_cvt_pk_bf16_f32 v13, v14, v15
	v_cvt_pk_bf16_f32 v14, v8, v9
	v_cvt_pk_bf16_f32 v15, v10, v11
	v_add_u32_e32 v230, 0x58000, v226
	global_store_dwordx4 v230, v[12:15], s[10:11]
	v_lshlrev_b32_e32 v214, 16, v188
	v_and_b32_e32 v215, 0xffff0000, v188
	v_lshlrev_b32_e32 v216, 16, v189
	v_and_b32_e32 v217, 0xffff0000, v189
	v_add_f32_e32 v4, v4, v214
	v_add_f32_e32 v5, v5, v215
	v_add_f32_e32 v6, v6, v216
	v_add_f32_e32 v7, v7, v217
	v_mul_f32_e32 v218, v5, v5
	v_mul_f32_e32 v219, v7, v7
	v_fmac_f32_e32 v218, v4, v4
	v_fmac_f32_e32 v219, v6, v6
	v_add_f32_e32 v222, v218, v219
	v_lshlrev_b32_e32 v214, 16, v190
	v_and_b32_e32 v215, 0xffff0000, v190
	v_lshlrev_b32_e32 v216, 16, v191
	v_and_b32_e32 v217, 0xffff0000, v191
	v_add_f32_e32 v0, v0, v214
	v_add_f32_e32 v1, v1, v215
	v_add_f32_e32 v2, v2, v216
	v_add_f32_e32 v3, v3, v217
	v_mul_f32_e32 v218, v1, v1
	v_mul_f32_e32 v219, v3, v3
	v_fmac_f32_e32 v218, v0, v0
	v_fmac_f32_e32 v219, v2, v2
	v_add_f32_e32 v223, v218, v219
	v_cvt_pk_bf16_f32 v4, v4, v5
	v_cvt_pk_bf16_f32 v5, v6, v7
	v_cvt_pk_bf16_f32 v6, v0, v1
	v_cvt_pk_bf16_f32 v7, v2, v3
	global_store_dwordx4 v230, v[4:7], s[10:11] offset:256
	v_add_f32_e32 v220, v220, v221
	v_add_f32_e32 v222, v222, v223
	v_add_f32_e32 v224, v220, v222
	ds_bpermute_b32 v225, v228, v224
	v_add_u32_e32 v231, 0x2c00, v227
	s_waitcnt lgkmcnt(0)
	v_add_f32_e32 v224, v224, v225
	ds_bpermute_b32 v225, v229, v224
	s_waitcnt lgkmcnt(0)
	v_add_f32_e32 v224, v224, v225
	s_and_saveexec_b64 s[0:1], vcc
	global_store_dword v231, v224, s[12:13]
	s_or_b64 exec, exec, s[0:1]
	s_mov_b64 s[42:43], -1
	s_andn2_b64 vcc, exec, s[20:21]
	s_mov_b64 s[0:1], -1
	s_cbranch_vccnz .LBB0_504
	s_andn2_b64 vcc, exec, s[8:9]
	s_cbranch_vccnz .LBB0_503
	s_barrier
	s_branch .LBB0_503

; __device__ __forceinline__ u32x4 pack8(const f32x4 v0, const f32x4 v1) { u32x4 w; w.x = cvt_pk_bf16(v0[0], v0[1]); w.y = cvt_pk_bf16(v0[2], v0[3]); w.z = cvt_pk_bf16(v1[0], v1[1]); w.w = cvt_pk_bf16(v1[2], v1[3]); return w; }
; __device__ __forceinline__ float sumsq8(const f32x4 a, const f32x4 b) { return ((a[0] * a[0] + a[1] * a[1]) + (a[2] * a[2] + a[3] * a[3])) + ((b[0] * b[0] + b[1] * b[1]) + (b[2] * b[2] + b[3] * b[3])); }
; __device__ __forceinline__ void unpack8(const u32x4 w, f32x4& a, f32x4& b) { a = (f32x4){bf_lo(w.x), bf_hi(w.x), bf_lo(w.y), bf_hi(w.y)}; b = (f32x4){bf_lo(w.z), bf_hi(w.z), bf_lo(w.w), bf_hi(w.w)}; }
;     __device__ __forceinline__ void operator()(const f32x4 (&acc)[2][2][4][2], const Unit& u, int wr, int wc, int fr, int fq) const {
;         const int row0 = u.pm * BM + wr * 64 + fr, col0 = u.pn * BM + wc * 32 + 8 * fq;
;         u32x4 rv[8][2];
; #pragma unroll
;         for (int i = 0; i < 8; ++i)
; #pragma unroll
;             for (int bj = 0; bj < 2; ++bj) rv[i][bj] = *(const u32x4*)(Rin + (size_t)(row0 + (i >> 2) * HALF + (i & 3) * 16) * DMODEL + col0 + bj * HALF);
; #pragma unroll
;         for (int ai = 0; ai < 2; ++ai)
; #pragma unroll
;             for (int m = 0; m < 4; ++m) { const int row = row0 + ai * HALF + m * 16; float part = 0.f;
; #pragma unroll
;                 for (int bj = 0; bj < 2; ++bj) { f32x4 r0, r1; unpack8(rv[ai * 4 + m][bj], r0, r1);
;                     const f32x4 h0 = r0 + acc[ai][bj][m][0], h1 = r1 + acc[ai][bj][m][1]; part += sumsq8(h0, h1);
;                     *(u32x4*)(XBo + (size_t)row * DMODEL + col0 + bj * HALF) = pack8(h0, h1); }
;                 part += __shfl_xor(part, 16); part += __shfl_xor(part, 32);
;                 if (fq == 0) ssq[(size_t)row * 16 + u.pn * 4 + wc] = part; }
;     }
.LBB0_968:
	v_readfirstlane_b32 s0, v192
	v_and_b32_e32 v224, 15, v192
	s_bfe_u32 s13, s0, 0x20006
	s_lshr_b32 s0, s0, 8
	s_lshl_b32 s0, s0, 6
	s_lshl_b32 s1, s24, 8
	s_add_i32 s0, s0, s1
	v_add_u32_e32 v224, s0, v224
	v_bfe_u32 v225, v192, 4, 2
	s_lshl_b32 s0, s22, 8
	s_lshl_b32 s1, s13, 5
	s_or_b32 s0, s0, s1
	v_lshl_or_b32 v232, v225, 3, s0
	v_lshlrev_b32_e32 v226, 11, v224
	v_lshl_add_u32 v226, v232, 1, v226
	v_mov_b32_e32 v230, v226
	global_load_dwordx4 v[116:119], v230, s[6:7]
	global_load_dwordx4 v[120:123], v230, s[6:7] offset:256
	v_add_u32_e32 v230, 0x8000, v226
	global_load_dwordx4 v[128:131], v230, s[6:7]
	global_load_dwordx4 v[132:135], v230, s[6:7] offset:256
	v_add_u32_e32 v230, 0x10000, v226
	global_load_dwordx4 v[136:139], v230, s[6:7]
	global_load_dwordx4 v[140:143], v230, s[6:7] offset:256
	v_add_u32_e32 v230, 0x18000, v226
	global_load_dwordx4 v[144:147], v230, s[6:7]
	global_load_dwordx4 v[156:159], v230, s[6:7] offset:256
	v_add_u32_e32 v230, 0x40000, v226
	global_load_dwordx4 v[160:163], v230, s[6:7]
	global_load_dwordx4 v[164:167], v230, s[6:7] offset:256
	v_add_u32_e32 v230, 0x48000, v226
	global_load_dwordx4 v[168:171], v230, s[6:7]
	global_load_dwordx4 v[172:175], v230, s[6:7] offset:256
	v_add_u32_e32 v230, 0x50000, v226
	global_load_dwordx4 v[176:179], v230, s[6:7]
	global_load_dwordx4 v[180:183], v230, s[6:7] offset:256
	v_add_u32_e32 v230, 0x58000, v226
	global_load_dwordx4 v[184:187], v230, s[6:7]
	global_load_dwordx4 v[188:191], v230, s[6:7] offset:256
	v_lshlrev_b32_e32 v227, 6, v224
	s_lshl_b32 s22, s22, 2
	s_ashr_i32 s23, s22, 31
	s_lshl_b32 s72, s13, 2
	s_lshl_b32 s0, s22, 2
	s_add_i32 s0, s0, s72
	v_add_u32_e32 v227, s0, v227
	v_cmp_eq_u32_e32 vcc, 0, v225
	v_xor_b32_e32 v228, 16, v241
	v_xor_b32_e32 v229, 32, v241
	v_lshlrev_b32_e32 v228, 2, v228
	v_lshlrev_b32_e32 v229, 2, v229
	s_waitcnt vmcnt(14)
	v_lshlrev_b32_e32 v214, 16, v116
	v_and_b32_e32 v215, 0xffff0000, v116
	v_lshlrev_b32_e32 v216, 16, v117
	v_and_b32_e32 v217, 0xffff0000, v117
	v_add_f32_e32 v152, v152, v214
	v_add_f32_e32 v153, v153, v215
	v_add_f32_e32 v154, v154, v216
	v_add_f32_e32 v155, v155, v217
	v_mul_f32_e32 v218, v153, v153
	v_mul_f32_e32 v219, v155, v155
	v_fmac_f32_e32 v218, v152, v152
	v_fmac_f32_e32 v219, v154, v154
	v_add_f32_e32 v220, v218, v219
	v_lshlrev_b32_e32 v214, 16, v118
	v_and_b32_e32 v215, 0xffff0000, v118
	v_lshlrev_b32_e32 v216, 16, v119
	v_and_b32_e32 v217, 0xffff0000, v119
	v_add_f32_e32 v148, v148, v214
	v_add_f32_e32 v149, v149, v215
	v_add_f32_e32 v150, v150, v216
	v_add_f32_e32 v151, v151, v217
	v_mul_f32_e32 v218, v149, v149
	v_mul_f32_e32 v219, v151, v151
	v_fmac_f32_e32 v218, v148, v148
	v_fmac_f32_e32 v219, v150, v150
	v_add_f32_e32 v221, v218, v219
	v_cvt_pk_bf16_f32 v152, v152, v153
	v_cvt_pk_bf16_f32 v153, v154, v155
	v_cvt_pk_bf16_f32 v154, v148, v149
	v_cvt_pk_bf16_f32 v155, v150, v151
	v_mov_b32_e32 v230, v226
	global_store_dwordx4 v230, v[152:155], s[6:7]
	v_lshlrev_b32_e32 v214, 16, v120
	v_and_b32_e32 v215, 0xffff0000, v120
	v_lshlrev_b32_e32 v216, 16, v121
	v_and_b32_e32 v217, 0xffff0000, v121
	v_add_f32_e32 v124, v124, v214
	v_add_f32_e32 v125, v125, v215
	v_add_f32_e32 v126, v126, v216
	v_add_f32_e32 v127, v127, v217
	v_mul_f32_e32 v218, v125, v125
	v_mul_f32_e32 v219, v127, v127
	v_fmac_f32_e32 v218, v124, v124
	v_fmac_f32_e32 v219, v126, v126
	v_add_f32_e32 v222, v218, v219
	v_lshlrev_b32_e32 v214, 16, v122
	v_and_b32_e32 v215, 0xffff0000, v122
	v_lshlrev_b32_e32 v216, 16, v123
	v_and_b32_e32 v217, 0xffff0000, v123
	v_add_f32_e32 v112, v112, v214
	v_add_f32_e32 v113, v113, v215
	v_add_f32_e32 v114, v114, v216
	v_add_f32_e32 v115, v115, v217
	v_mul_f32_e32 v218, v113, v113
	v_mul_f32_e32 v219, v115, v115
	v_fmac_f32_e32 v218, v112, v112
	v_fmac_f32_e32 v219, v114, v114
	v_add_f32_e32 v223, v218, v219
	v_cvt_pk_bf16_f32 v124, v124, v125
	v_cvt_pk_bf16_f32 v125, v126, v127
	v_cvt_pk_bf16_f32 v126, v112, v113
	v_cvt_pk_bf16_f32 v127, v114, v115
	global_store_dwordx4 v230, v[124:127], s[6:7] offset:256
	v_add_f32_e32 v220, v220, v221
	v_add_f32_e32 v222, v222, v223
	v_add_f32_e32 v224, v220, v222
	ds_bpermute_b32 v225, v228, v224
	v_mov_b32_e32 v231, v227
	s_waitcnt lgkmcnt(0)
	v_add_f32_e32 v224, v224, v225
	ds_bpermute_b32 v225, v229, v224
	s_waitcnt lgkmcnt(0)
	v_add_f32_e32 v224, v224, v225
	s_and_saveexec_b64 s[0:1], vcc
	global_store_dword v231, v224, s[8:9]
	s_or_b64 exec, exec, s[0:1]
	s_waitcnt vmcnt(15)
	v_lshlrev_b32_e32 v214, 16, v128
	v_and_b32_e32 v215, 0xffff0000, v128
	v_lshlrev_b32_e32 v216, 16, v129
	v_and_b32_e32 v217, 0xffff0000, v129
	v_add_f32_e32 v108, v108, v214
	v_add_f32_e32 v109, v109, v215
	v_add_f32_e32 v110, v110, v216
	v_add_f32_e32 v111, v111, v217
	v_mul_f32_e32 v218, v109, v109
	v_mul_f32_e32 v219, v111, v111
	v_fmac_f32_e32 v218, v108, v108
	v_fmac_f32_e32 v219, v110, v110
	v_add_f32_e32 v220, v218, v219
	v_lshlrev_b32_e32 v214, 16, v130
	v_and_b32_e32 v215, 0xffff0000, v130
	v_lshlrev_b32_e32 v216, 16, v131
	v_and_b32_e32 v217, 0xffff0000, v131
	v_add_f32_e32 v104, v104, v214
	v_add_f32_e32 v105, v105, v215
	v_add_f32_e32 v106, v106, v216
	v_add_f32_e32 v107, v107, v217
	v_mul_f32_e32 v218, v105, v105
	v_mul_f32_e32 v219, v107, v107
	v_fmac_f32_e32 v218, v104, v104
	v_fmac_f32_e32 v219, v106, v106
	v_add_f32_e32 v221, v218, v219
	v_cvt_pk_bf16_f32 v108, v108, v109
	v_cvt_pk_bf16_f32 v109, v110, v111
	v_cvt_pk_bf16_f32 v110, v104, v105
	v_cvt_pk_bf16_f32 v111, v106, v107
	v_add_u32_e32 v230, 0x8000, v226
	global_store_dwordx4 v230, v[108:111], s[6:7]
	v_lshlrev_b32_e32 v214, 16, v132
	v_and_b32_e32 v215, 0xffff0000, v132
	v_lshlrev_b32_e32 v216, 16, v133
	v_and_b32_e32 v217, 0xffff0000, v133
	v_add_f32_e32 v100, v100, v214
	v_add_f32_e32 v101, v101, v215
	v_add_f32_e32 v102, v102, v216
	v_add_f32_e32 v103, v103, v217
	v_mul_f32_e32 v218, v101, v101
	v_mul_f32_e32 v219, v103, v103
	v_fmac_f32_e32 v218, v100, v100
	v_fmac_f32_e32 v219, v102, v102
	v_add_f32_e32 v222, v218, v219
	v_lshlrev_b32_e32 v214, 16, v134
	v_and_b32_e32 v215, 0xffff0000, v134
	v_lshlrev_b32_e32 v216, 16, v135
	v_and_b32_e32 v217, 0xffff0000, v135
	v_add_f32_e32 v96, v96, v214
	v_add_f32_e32 v97, v97, v215
	v_add_f32_e32 v98, v98, v216
	v_add_f32_e32 v99, v99, v217
	v_mul_f32_e32 v218, v97, v97
	v_mul_f32_e32 v219, v99, v99
	v_fmac_f32_e32 v218, v96, v96
	v_fmac_f32_e32 v219, v98, v98
	v_add_f32_e32 v223, v218, v219
	v_cvt_pk_bf16_f32 v100, v100, v101
	v_cvt_pk_bf16_f32 v101, v102, v103
	v_cvt_pk_bf16_f32 v102, v96, v97
	v_cvt_pk_bf16_f32 v103, v98, v99
	global_store_dwordx4 v230, v[100:103], s[6:7] offset:256
	v_add_f32_e32 v220, v220, v221
	v_add_f32_e32 v222, v222, v223
	v_add_f32_e32 v224, v220, v222
	ds_bpermute_b32 v225, v228, v224
	v_add_u32_e32 v231, 0x400, v227
	s_waitcnt lgkmcnt(0)
; __device__ __forceinline__ u32x4 pack8(const f32x4 v0, const f32x4 v1) { u32x4 w; w.x = cvt_pk_bf16(v0[0], v0[1]); w.y = cvt_pk_bf16(v0[2], v0[3]); w.z = cvt_pk_bf16(v1[0], v1[1]); w.w = cvt_pk_bf16(v1[2], v1[3]); return w; }
; __device__ __forceinline__ float sumsq8(const f32x4 a, const f32x4 b) { return ((a[0] * a[0] + a[1] * a[1]) + (a[2] * a[2] + a[3] * a[3])) + ((b[0] * b[0] + b[1] * b[1]) + (b[2] * b[2] + b[3] * b[3])); }
; __device__ __forceinline__ void unpack8(const u32x4 w, f32x4& a, f32x4& b) { a = (f32x4){bf_lo(w.x), bf_hi(w.x), bf_lo(w.y), bf_hi(w.y)}; b = (f32x4){bf_lo(w.z), bf_hi(w.z), bf_lo(w.w), bf_hi(w.w)}; }
;     __device__ __forceinline__ void operator()(const f32x4 (&acc)[2][2][4][2], const Unit& u, int wr, int wc, int fr, int fq) const {
;     ...
;             for (int m = 0; m < 4; ++m) { const int row = row0 + ai * HALF + m * 16; float part = 0.f;
; #pragma unroll
;                 for (int bj = 0; bj < 2; ++bj) { f32x4 r0, r1; unpack8(rv[ai * 4 + m][bj], r0, r1);
;                     const f32x4 h0 = r0 + acc[ai][bj][m][0], h1 = r1 + acc[ai][bj][m][1]; part += sumsq8(h0, h1);
;                     *(u32x4*)(XBo + (size_t)row * DMODEL + col0 + bj * HALF) = pack8(h0, h1); }
;                 part += __shfl_xor(part, 16); part += __shfl_xor(part, 32);
;                 if (fq == 0) ssq[(size_t)row * 16 + u.pn * 4 + wc] = part; }
	v_add_f32_e32 v224, v224, v225
	ds_bpermute_b32 v225, v229, v224
	s_waitcnt lgkmcnt(0)
	v_add_f32_e32 v224, v224, v225
	s_and_saveexec_b64 s[0:1], vcc
	global_store_dword v231, v224, s[8:9]
	s_or_b64 exec, exec, s[0:1]
	s_waitcnt vmcnt(16)
	v_lshlrev_b32_e32 v214, 16, v136
	v_and_b32_e32 v215, 0xffff0000, v136
	v_lshlrev_b32_e32 v216, 16, v137
	v_and_b32_e32 v217, 0xffff0000, v137
	v_add_f32_e32 v92, v92, v214
	v_add_f32_e32 v93, v93, v215
	v_add_f32_e32 v94, v94, v216
	v_add_f32_e32 v95, v95, v217
	v_mul_f32_e32 v218, v93, v93
	v_mul_f32_e32 v219, v95, v95
	v_fmac_f32_e32 v218, v92, v92
	v_fmac_f32_e32 v219, v94, v94
	v_add_f32_e32 v220, v218, v219
	v_lshlrev_b32_e32 v214, 16, v138
	v_and_b32_e32 v215, 0xffff0000, v138
	v_lshlrev_b32_e32 v216, 16, v139
	v_and_b32_e32 v217, 0xffff0000, v139
	v_add_f32_e32 v88, v88, v214
	v_add_f32_e32 v89, v89, v215
	v_add_f32_e32 v90, v90, v216
	v_add_f32_e32 v91, v91, v217
	v_mul_f32_e32 v218, v89, v89
	v_mul_f32_e32 v219, v91, v91
	v_fmac_f32_e32 v218, v88, v88
	v_fmac_f32_e32 v219, v90, v90
	v_add_f32_e32 v221, v218, v219
	v_cvt_pk_bf16_f32 v92, v92, v93
	v_cvt_pk_bf16_f32 v93, v94, v95
	v_cvt_pk_bf16_f32 v94, v88, v89
	v_cvt_pk_bf16_f32 v95, v90, v91
	v_add_u32_e32 v230, 0x10000, v226
	global_store_dwordx4 v230, v[92:95], s[6:7]
	v_lshlrev_b32_e32 v214, 16, v140
	v_and_b32_e32 v215, 0xffff0000, v140
	v_lshlrev_b32_e32 v216, 16, v141
	v_and_b32_e32 v217, 0xffff0000, v141
	v_add_f32_e32 v84, v84, v214
	v_add_f32_e32 v85, v85, v215
	v_add_f32_e32 v86, v86, v216
	v_add_f32_e32 v87, v87, v217
	v_mul_f32_e32 v218, v85, v85
	v_mul_f32_e32 v219, v87, v87
	v_fmac_f32_e32 v218, v84, v84
	v_fmac_f32_e32 v219, v86, v86
	v_add_f32_e32 v222, v218, v219
	v_lshlrev_b32_e32 v214, 16, v142
	v_and_b32_e32 v215, 0xffff0000, v142
	v_lshlrev_b32_e32 v216, 16, v143
	v_and_b32_e32 v217, 0xffff0000, v143
	v_add_f32_e32 v80, v80, v214
	v_add_f32_e32 v81, v81, v215
	v_add_f32_e32 v82, v82, v216
	v_add_f32_e32 v83, v83, v217
	v_mul_f32_e32 v218, v81, v81
	v_mul_f32_e32 v219, v83, v83
	v_fmac_f32_e32 v218, v80, v80
	v_fmac_f32_e32 v219, v82, v82
	v_add_f32_e32 v223, v218, v219
	v_cvt_pk_bf16_f32 v84, v84, v85
	v_cvt_pk_bf16_f32 v85, v86, v87
	v_cvt_pk_bf16_f32 v86, v80, v81
	v_cvt_pk_bf16_f32 v87, v82, v83
	global_store_dwordx4 v230, v[84:87], s[6:7] offset:256
	v_add_f32_e32 v220, v220, v221
	v_add_f32_e32 v222, v222, v223
	v_add_f32_e32 v224, v220, v222
	ds_bpermute_b32 v225, v228, v224
	v_add_u32_e32 v231, 0x800, v227
	s_waitcnt lgkmcnt(0)
	v_add_f32_e32 v224, v224, v225
	ds_bpermute_b32 v225, v229, v224
	s_waitcnt lgkmcnt(0)
	v_add_f32_e32 v224, v224, v225
	s_and_saveexec_b64 s[0:1], vcc
	global_store_dword v231, v224, s[8:9]
	s_or_b64 exec, exec, s[0:1]
	s_waitcnt vmcnt(17)
	v_lshlrev_b32_e32 v214, 16, v144
	v_and_b32_e32 v215, 0xffff0000, v144
	v_lshlrev_b32_e32 v216, 16, v145
	v_and_b32_e32 v217, 0xffff0000, v145
	v_add_f32_e32 v76, v76, v214
	v_add_f32_e32 v77, v77, v215
	v_add_f32_e32 v78, v78, v216
	v_add_f32_e32 v79, v79, v217
	v_mul_f32_e32 v218, v77, v77
	v_mul_f32_e32 v219, v79, v79
	v_fmac_f32_e32 v218, v76, v76
	v_fmac_f32_e32 v219, v78, v78
	v_add_f32_e32 v220, v218, v219
	v_lshlrev_b32_e32 v214, 16, v146
	v_and_b32_e32 v215, 0xffff0000, v146
	v_lshlrev_b32_e32 v216, 16, v147
	v_and_b32_e32 v217, 0xffff0000, v147
	v_add_f32_e32 v72, v72, v214
	v_add_f32_e32 v73, v73, v215
	v_add_f32_e32 v74, v74, v216
	v_add_f32_e32 v75, v75, v217
	v_mul_f32_e32 v218, v73, v73
	v_mul_f32_e32 v219, v75, v75
	v_fmac_f32_e32 v218, v72, v72
	v_fmac_f32_e32 v219, v74, v74
	v_add_f32_e32 v221, v218, v219
	v_cvt_pk_bf16_f32 v76, v76, v77
	v_cvt_pk_bf16_f32 v77, v78, v79
	v_cvt_pk_bf16_f32 v78, v72, v73
	v_cvt_pk_bf16_f32 v79, v74, v75
	v_add_u32_e32 v230, 0x18000, v226
	global_store_dwordx4 v230, v[76:79], s[6:7]
	v_lshlrev_b32_e32 v214, 16, v156
	v_and_b32_e32 v215, 0xffff0000, v156
	v_lshlrev_b32_e32 v216, 16, v157
	v_and_b32_e32 v217, 0xffff0000, v157
	v_add_f32_e32 v68, v68, v214
	v_add_f32_e32 v69, v69, v215
	v_add_f32_e32 v70, v70, v216
	v_add_f32_e32 v71, v71, v217
	v_mul_f32_e32 v218, v69, v69
	v_mul_f32_e32 v219, v71, v71
	v_fmac_f32_e32 v218, v68, v68
	v_fmac_f32_e32 v219, v70, v70
	v_add_f32_e32 v222, v218, v219
	v_lshlrev_b32_e32 v214, 16, v158
	v_and_b32_e32 v215, 0xffff0000, v158
	v_lshlrev_b32_e32 v216, 16, v159
	v_and_b32_e32 v217, 0xffff0000, v159
	v_add_f32_e32 v64, v64, v214
	v_add_f32_e32 v65, v65, v215
	v_add_f32_e32 v66, v66, v216
	v_add_f32_e32 v67, v67, v217
	v_mul_f32_e32 v218, v65, v65
	v_mul_f32_e32 v219, v67, v67
	v_fmac_f32_e32 v218, v64, v64
	v_fmac_f32_e32 v219, v66, v66
	v_add_f32_e32 v223, v218, v219
	v_cvt_pk_bf16_f32 v68, v68, v69
	v_cvt_pk_bf16_f32 v69, v70, v71
	v_cvt_pk_bf16_f32 v70, v64, v65
	v_cvt_pk_bf16_f32 v71, v66, v67
	global_store_dwordx4 v230, v[68:71], s[6:7] offset:256
	v_add_f32_e32 v220, v220, v221
	v_add_f32_e32 v222, v222, v223
	v_add_f32_e32 v224, v220, v222
	ds_bpermute_b32 v225, v228, v224
	v_add_u32_e32 v231, 0xc00, v227
	s_waitcnt lgkmcnt(0)
	v_add_f32_e32 v224, v224, v225
	ds_bpermute_b32 v225, v229, v224
	s_waitcnt lgkmcnt(0)
	v_add_f32_e32 v224, v224, v225
	s_and_saveexec_b64 s[0:1], vcc
	global_store_dword v231, v224, s[8:9]
	s_or_b64 exec, exec, s[0:1]
	s_waitcnt vmcnt(18)
; __device__ __forceinline__ u32x4 pack8(const f32x4 v0, const f32x4 v1) { u32x4 w; w.x = cvt_pk_bf16(v0[0], v0[1]); w.y = cvt_pk_bf16(v0[2], v0[3]); w.z = cvt_pk_bf16(v1[0], v1[1]); w.w = cvt_pk_bf16(v1[2], v1[3]); return w; }
; __device__ __forceinline__ float sumsq8(const f32x4 a, const f32x4 b) { return ((a[0] * a[0] + a[1] * a[1]) + (a[2] * a[2] + a[3] * a[3])) + ((b[0] * b[0] + b[1] * b[1]) + (b[2] * b[2] + b[3] * b[3])); }
; __device__ __forceinline__ void unpack8(const u32x4 w, f32x4& a, f32x4& b) { a = (f32x4){bf_lo(w.x), bf_hi(w.x), bf_lo(w.y), bf_hi(w.y)}; b = (f32x4){bf_lo(w.z), bf_hi(w.z), bf_lo(w.w), bf_hi(w.w)}; }
;     __device__ __forceinline__ void operator()(const f32x4 (&acc)[2][2][4][2], const Unit& u, int wr, int wc, int fr, int fq) const {
;     ...
;             for (int m = 0; m < 4; ++m) { const int row = row0 + ai * HALF + m * 16; float part = 0.f;
; #pragma unroll
;                 for (int bj = 0; bj < 2; ++bj) { f32x4 r0, r1; unpack8(rv[ai * 4 + m][bj], r0, r1);
;                     const f32x4 h0 = r0 + acc[ai][bj][m][0], h1 = r1 + acc[ai][bj][m][1]; part += sumsq8(h0, h1);
;                     *(u32x4*)(XBo + (size_t)row * DMODEL + col0 + bj * HALF) = pack8(h0, h1); }
;                 part += __shfl_xor(part, 16); part += __shfl_xor(part, 32);
;                 if (fq == 0) ssq[(size_t)row * 16 + u.pn * 4 + wc] = part; }
	v_lshlrev_b32_e32 v214, 16, v160
	v_and_b32_e32 v215, 0xffff0000, v160
	v_lshlrev_b32_e32 v216, 16, v161
	v_and_b32_e32 v217, 0xffff0000, v161
	v_add_f32_e32 v60, v60, v214
	v_add_f32_e32 v61, v61, v215
	v_add_f32_e32 v62, v62, v216
	v_add_f32_e32 v63, v63, v217
	v_mul_f32_e32 v218, v61, v61
	v_mul_f32_e32 v219, v63, v63
	v_fmac_f32_e32 v218, v60, v60
	v_fmac_f32_e32 v219, v62, v62
	v_add_f32_e32 v220, v218, v219
	v_lshlrev_b32_e32 v214, 16, v162
	v_and_b32_e32 v215, 0xffff0000, v162
	v_lshlrev_b32_e32 v216, 16, v163
	v_and_b32_e32 v217, 0xffff0000, v163
	v_add_f32_e32 v56, v56, v214
	v_add_f32_e32 v57, v57, v215
	v_add_f32_e32 v58, v58, v216
	v_add_f32_e32 v59, v59, v217
	v_mul_f32_e32 v218, v57, v57
	v_mul_f32_e32 v219, v59, v59
	v_fmac_f32_e32 v218, v56, v56
	v_fmac_f32_e32 v219, v58, v58
	v_add_f32_e32 v221, v218, v219
	v_cvt_pk_bf16_f32 v60, v60, v61
	v_cvt_pk_bf16_f32 v61, v62, v63
	v_cvt_pk_bf16_f32 v62, v56, v57
	v_cvt_pk_bf16_f32 v63, v58, v59
	v_add_u32_e32 v230, 0x40000, v226
	global_store_dwordx4 v230, v[60:63], s[6:7]
	v_lshlrev_b32_e32 v214, 16, v164
	v_and_b32_e32 v215, 0xffff0000, v164
	v_lshlrev_b32_e32 v216, 16, v165
	v_and_b32_e32 v217, 0xffff0000, v165
	v_add_f32_e32 v52, v52, v214
	v_add_f32_e32 v53, v53, v215
	v_add_f32_e32 v54, v54, v216
	v_add_f32_e32 v55, v55, v217
	v_mul_f32_e32 v218, v53, v53
	v_mul_f32_e32 v219, v55, v55
	v_fmac_f32_e32 v218, v52, v52
	v_fmac_f32_e32 v219, v54, v54
	v_add_f32_e32 v222, v218, v219
	v_lshlrev_b32_e32 v214, 16, v166
	v_and_b32_e32 v215, 0xffff0000, v166
	v_lshlrev_b32_e32 v216, 16, v167
	v_and_b32_e32 v217, 0xffff0000, v167
	v_add_f32_e32 v48, v48, v214
	v_add_f32_e32 v49, v49, v215
	v_add_f32_e32 v50, v50, v216
	v_add_f32_e32 v51, v51, v217
	v_mul_f32_e32 v218, v49, v49
	v_mul_f32_e32 v219, v51, v51
	v_fmac_f32_e32 v218, v48, v48
	v_fmac_f32_e32 v219, v50, v50
	v_add_f32_e32 v223, v218, v219
	v_cvt_pk_bf16_f32 v52, v52, v53
	v_cvt_pk_bf16_f32 v53, v54, v55
	v_cvt_pk_bf16_f32 v54, v48, v49
	v_cvt_pk_bf16_f32 v55, v50, v51
	global_store_dwordx4 v230, v[52:55], s[6:7] offset:256
	v_add_f32_e32 v220, v220, v221
	v_add_f32_e32 v222, v222, v223
	v_add_f32_e32 v224, v220, v222
	ds_bpermute_b32 v225, v228, v224
	v_add_u32_e32 v231, 0x2000, v227
	s_waitcnt lgkmcnt(0)
	v_add_f32_e32 v224, v224, v225
	ds_bpermute_b32 v225, v229, v224
	s_waitcnt lgkmcnt(0)
	v_add_f32_e32 v224, v224, v225
	s_and_saveexec_b64 s[0:1], vcc
	global_store_dword v231, v224, s[8:9]
	s_or_b64 exec, exec, s[0:1]
	s_waitcnt vmcnt(19)
	v_lshlrev_b32_e32 v214, 16, v168
	v_and_b32_e32 v215, 0xffff0000, v168
	v_lshlrev_b32_e32 v216, 16, v169
	v_and_b32_e32 v217, 0xffff0000, v169
	v_add_f32_e32 v44, v44, v214
	v_add_f32_e32 v45, v45, v215
	v_add_f32_e32 v46, v46, v216
	v_add_f32_e32 v47, v47, v217
	v_mul_f32_e32 v218, v45, v45
	v_mul_f32_e32 v219, v47, v47
	v_fmac_f32_e32 v218, v44, v44
	v_fmac_f32_e32 v219, v46, v46
	v_add_f32_e32 v220, v218, v219
	v_lshlrev_b32_e32 v214, 16, v170
	v_and_b32_e32 v215, 0xffff0000, v170
	v_lshlrev_b32_e32 v216, 16, v171
	v_and_b32_e32 v217, 0xffff0000, v171
	v_add_f32_e32 v40, v40, v214
	v_add_f32_e32 v41, v41, v215
	v_add_f32_e32 v42, v42, v216
	v_add_f32_e32 v43, v43, v217
	v_mul_f32_e32 v218, v41, v41
	v_mul_f32_e32 v219, v43, v43
	v_fmac_f32_e32 v218, v40, v40
	v_fmac_f32_e32 v219, v42, v42
	v_add_f32_e32 v221, v218, v219
	v_cvt_pk_bf16_f32 v44, v44, v45
	v_cvt_pk_bf16_f32 v45, v46, v47
	v_cvt_pk_bf16_f32 v46, v40, v41
	v_cvt_pk_bf16_f32 v47, v42, v43
	v_add_u32_e32 v230, 0x48000, v226
	global_store_dwordx4 v230, v[44:47], s[6:7]
	v_lshlrev_b32_e32 v214, 16, v172
	v_and_b32_e32 v215, 0xffff0000, v172
	v_lshlrev_b32_e32 v216, 16, v173
	v_and_b32_e32 v217, 0xffff0000, v173
	v_add_f32_e32 v36, v36, v214
	v_add_f32_e32 v37, v37, v215
	v_add_f32_e32 v38, v38, v216
	v_add_f32_e32 v39, v39, v217
	v_mul_f32_e32 v218, v37, v37
	v_mul_f32_e32 v219, v39, v39
	v_fmac_f32_e32 v218, v36, v36
	v_fmac_f32_e32 v219, v38, v38
	v_add_f32_e32 v222, v218, v219
	v_lshlrev_b32_e32 v214, 16, v174
	v_and_b32_e32 v215, 0xffff0000, v174
	v_lshlrev_b32_e32 v216, 16, v175
	v_and_b32_e32 v217, 0xffff0000, v175
	v_add_f32_e32 v32, v32, v214
	v_add_f32_e32 v33, v33, v215
	v_add_f32_e32 v34, v34, v216
	v_add_f32_e32 v35, v35, v217
	v_mul_f32_e32 v218, v33, v33
	v_mul_f32_e32 v219, v35, v35
	v_fmac_f32_e32 v218, v32, v32
	v_fmac_f32_e32 v219, v34, v34
	v_add_f32_e32 v223, v218, v219
	v_cvt_pk_bf16_f32 v36, v36, v37
	v_cvt_pk_bf16_f32 v37, v38, v39
	v_cvt_pk_bf16_f32 v38, v32, v33
	v_cvt_pk_bf16_f32 v39, v34, v35
	global_store_dwordx4 v230, v[36:39], s[6:7] offset:256
	v_add_f32_e32 v220, v220, v221
	v_add_f32_e32 v222, v222, v223
	v_add_f32_e32 v224, v220, v222
	ds_bpermute_b32 v225, v228, v224
	v_add_u32_e32 v231, 0x2400, v227
	s_waitcnt lgkmcnt(0)
	v_add_f32_e32 v224, v224, v225
	ds_bpermute_b32 v225, v229, v224
	s_waitcnt lgkmcnt(0)
	v_add_f32_e32 v224, v224, v225
	s_and_saveexec_b64 s[0:1], vcc
	global_store_dword v231, v224, s[8:9]
	s_or_b64 exec, exec, s[0:1]
	s_waitcnt vmcnt(20)
; __device__ __forceinline__ u32x4 pack8(const f32x4 v0, const f32x4 v1) { u32x4 w; w.x = cvt_pk_bf16(v0[0], v0[1]); w.y = cvt_pk_bf16(v0[2], v0[3]); w.z = cvt_pk_bf16(v1[0], v1[1]); w.w = cvt_pk_bf16(v1[2], v1[3]); return w; }
; __device__ __forceinline__ float sumsq8(const f32x4 a, const f32x4 b) { return ((a[0] * a[0] + a[1] * a[1]) + (a[2] * a[2] + a[3] * a[3])) + ((b[0] * b[0] + b[1] * b[1]) + (b[2] * b[2] + b[3] * b[3])); }
; __device__ __forceinline__ void unpack8(const u32x4 w, f32x4& a, f32x4& b) { a = (f32x4){bf_lo(w.x), bf_hi(w.x), bf_lo(w.y), bf_hi(w.y)}; b = (f32x4){bf_lo(w.z), bf_hi(w.z), bf_lo(w.w), bf_hi(w.w)}; }
;     __device__ __forceinline__ void operator()(const f32x4 (&acc)[2][2][4][2], const Unit& u, int wr, int wc, int fr, int fq) const {
;     ...
; #pragma unroll
;         for (int ai = 0; ai < 2; ++ai)
; #pragma unroll
;             for (int m = 0; m < 4; ++m) { const int row = row0 + ai * HALF + m * 16; float part = 0.f;
; #pragma unroll
;                 for (int bj = 0; bj < 2; ++bj) { f32x4 r0, r1; unpack8(rv[ai * 4 + m][bj], r0, r1);
;                     const f32x4 h0 = r0 + acc[ai][bj][m][0], h1 = r1 + acc[ai][bj][m][1]; part += sumsq8(h0, h1);
;                     *(u32x4*)(XBo + (size_t)row * DMODEL + col0 + bj * HALF) = pack8(h0, h1); }
;                 part += __shfl_xor(part, 16); part += __shfl_xor(part, 32);
;                 if (fq == 0) ssq[(size_t)row * 16 + u.pn * 4 + wc] = part; }
	v_lshlrev_b32_e32 v214, 16, v176
	v_and_b32_e32 v215, 0xffff0000, v176
	v_lshlrev_b32_e32 v216, 16, v177
	v_and_b32_e32 v217, 0xffff0000, v177
	v_add_f32_e32 v28, v28, v214
	v_add_f32_e32 v29, v29, v215
	v_add_f32_e32 v30, v30, v216
	v_add_f32_e32 v31, v31, v217
	v_mul_f32_e32 v218, v29, v29
	v_mul_f32_e32 v219, v31, v31
	v_fmac_f32_e32 v218, v28, v28
	v_fmac_f32_e32 v219, v30, v30
	v_add_f32_e32 v220, v218, v219
	v_lshlrev_b32_e32 v214, 16, v178
	v_and_b32_e32 v215, 0xffff0000, v178
	v_lshlrev_b32_e32 v216, 16, v179
	v_and_b32_e32 v217, 0xffff0000, v179
	v_add_f32_e32 v24, v24, v214
	v_add_f32_e32 v25, v25, v215
	v_add_f32_e32 v26, v26, v216
	v_add_f32_e32 v27, v27, v217
	v_mul_f32_e32 v218, v25, v25
	v_mul_f32_e32 v219, v27, v27
	v_fmac_f32_e32 v218, v24, v24
	v_fmac_f32_e32 v219, v26, v26
	v_add_f32_e32 v221, v218, v219
	v_cvt_pk_bf16_f32 v28, v28, v29
	v_cvt_pk_bf16_f32 v29, v30, v31
	v_cvt_pk_bf16_f32 v30, v24, v25
	v_cvt_pk_bf16_f32 v31, v26, v27
	v_add_u32_e32 v230, 0x50000, v226
	global_store_dwordx4 v230, v[28:31], s[6:7]
	v_lshlrev_b32_e32 v214, 16, v180
	v_and_b32_e32 v215, 0xffff0000, v180
	v_lshlrev_b32_e32 v216, 16, v181
	v_and_b32_e32 v217, 0xffff0000, v181
	v_add_f32_e32 v20, v20, v214
	v_add_f32_e32 v21, v21, v215
	v_add_f32_e32 v22, v22, v216
	v_add_f32_e32 v23, v23, v217
	v_mul_f32_e32 v218, v21, v21
	v_mul_f32_e32 v219, v23, v23
	v_fmac_f32_e32 v218, v20, v20
	v_fmac_f32_e32 v219, v22, v22
	v_add_f32_e32 v222, v218, v219
	v_lshlrev_b32_e32 v214, 16, v182
	v_and_b32_e32 v215, 0xffff0000, v182
	v_lshlrev_b32_e32 v216, 16, v183
	v_and_b32_e32 v217, 0xffff0000, v183
	v_add_f32_e32 v16, v16, v214
	v_add_f32_e32 v17, v17, v215
	v_add_f32_e32 v18, v18, v216
	v_add_f32_e32 v19, v19, v217
	v_mul_f32_e32 v218, v17, v17
	v_mul_f32_e32 v219, v19, v19
	v_fmac_f32_e32 v218, v16, v16
	v_fmac_f32_e32 v219, v18, v18
	v_add_f32_e32 v223, v218, v219
	v_cvt_pk_bf16_f32 v20, v20, v21
	v_cvt_pk_bf16_f32 v21, v22, v23
	v_cvt_pk_bf16_f32 v22, v16, v17
	v_cvt_pk_bf16_f32 v23, v18, v19
	global_store_dwordx4 v230, v[20:23], s[6:7] offset:256
	v_add_f32_e32 v220, v220, v221
	v_add_f32_e32 v222, v222, v223
	v_add_f32_e32 v224, v220, v222
	ds_bpermute_b32 v225, v228, v224
	v_add_u32_e32 v231, 0x2800, v227
	s_waitcnt lgkmcnt(0)
	v_add_f32_e32 v224, v224, v225
	ds_bpermute_b32 v225, v229, v224
	s_waitcnt lgkmcnt(0)
	v_add_f32_e32 v224, v224, v225
	s_and_saveexec_b64 s[0:1], vcc
	global_store_dword v231, v224, s[8:9]
	s_or_b64 exec, exec, s[0:1]
	s_waitcnt vmcnt(21)
	v_lshlrev_b32_e32 v214, 16, v184
	v_and_b32_e32 v215, 0xffff0000, v184
	v_lshlrev_b32_e32 v216, 16, v185
	v_and_b32_e32 v217, 0xffff0000, v185
	v_add_f32_e32 v12, v12, v214
	v_add_f32_e32 v13, v13, v215
	v_add_f32_e32 v14, v14, v216
	v_add_f32_e32 v15, v15, v217
	v_mul_f32_e32 v218, v13, v13
	v_mul_f32_e32 v219, v15, v15
	v_fmac_f32_e32 v218, v12, v12
	v_fmac_f32_e32 v219, v14, v14
	v_add_f32_e32 v220, v218, v219
	v_lshlrev_b32_e32 v214, 16, v186
	v_and_b32_e32 v215, 0xffff0000, v186
	v_lshlrev_b32_e32 v216, 16, v187
	v_and_b32_e32 v217, 0xffff0000, v187
	v_add_f32_e32 v8, v8, v214
	v_add_f32_e32 v9, v9, v215
	v_add_f32_e32 v10, v10, v216
	v_add_f32_e32 v11, v11, v217
	v_mul_f32_e32 v218, v9, v9
	v_mul_f32_e32 v219, v11, v11
	v_fmac_f32_e32 v218, v8, v8
	v_fmac_f32_e32 v219, v10, v10
	v_add_f32_e32 v221, v218, v219
	v_cvt_pk_bf16_f32 v12, v12, v13
	v_cvt_pk_bf16_f32 v13, v14, v15
	v_cvt_pk_bf16_f32 v14, v8, v9
	v_cvt_pk_bf16_f32 v15, v10, v11
	v_add_u32_e32 v230, 0x58000, v226
	global_store_dwordx4 v230, v[12:15], s[6:7]
	v_lshlrev_b32_e32 v214, 16, v188
	v_and_b32_e32 v215, 0xffff0000, v188
	v_lshlrev_b32_e32 v216, 16, v189
	v_and_b32_e32 v217, 0xffff0000, v189
	v_add_f32_e32 v4, v4, v214
	v_add_f32_e32 v5, v5, v215
	v_add_f32_e32 v6, v6, v216
	v_add_f32_e32 v7, v7, v217
	v_mul_f32_e32 v218, v5, v5
	v_mul_f32_e32 v219, v7, v7
	v_fmac_f32_e32 v218, v4, v4
	v_fmac_f32_e32 v219, v6, v6
	v_add_f32_e32 v222, v218, v219
	v_lshlrev_b32_e32 v214, 16, v190
	v_and_b32_e32 v215, 0xffff0000, v190
	v_lshlrev_b32_e32 v216, 16, v191
	v_and_b32_e32 v217, 0xffff0000, v191
	v_add_f32_e32 v0, v0, v214
	v_add_f32_e32 v1, v1, v215
	v_add_f32_e32 v2, v2, v216
	v_add_f32_e32 v3, v3, v217
	v_mul_f32_e32 v218, v1, v1
	v_mul_f32_e32 v219, v3, v3
	v_fmac_f32_e32 v218, v0, v0
	v_fmac_f32_e32 v219, v2, v2
	v_add_f32_e32 v223, v218, v219
	v_cvt_pk_bf16_f32 v4, v4, v5
	v_cvt_pk_bf16_f32 v5, v6, v7
	v_cvt_pk_bf16_f32 v6, v0, v1
	v_cvt_pk_bf16_f32 v7, v2, v3
	global_store_dwordx4 v230, v[4:7], s[6:7] offset:256
	v_add_f32_e32 v220, v220, v221
	v_add_f32_e32 v222, v222, v223
	v_add_f32_e32 v224, v220, v222
	ds_bpermute_b32 v225, v228, v224
	v_add_u32_e32 v231, 0x2c00, v227
	s_waitcnt lgkmcnt(0)
	v_add_f32_e32 v224, v224, v225
	ds_bpermute_b32 v225, v229, v224
	s_waitcnt lgkmcnt(0)
	v_add_f32_e32 v224, v224, v225
	s_and_saveexec_b64 s[0:1], vcc
	global_store_dword v231, v224, s[8:9]
	s_or_b64 exec, exec, s[0:1]
	s_mov_b64 s[26:27], -1
	s_andn2_b64 vcc, exec, s[16:17]
	s_mov_b64 s[0:1], -1
	s_cbranch_vccnz .LBB0_955
	s_andn2_b64 vcc, exec, s[4:5]
	s_cbranch_vccnz .LBB0_954
	s_barrier
	s_branch .LBB0_954
